# layer-1 gate/up weight conversion riding in layer 0's input-projection phase: the two items sharing 128-byte source spans are converted by one wave (full-line row loads), pipelined loop
# baseline (speedup 1.0000x reference)
.Lcva_done:
.LBB0_562:
	s_cmp_eq_u32 s80, 2
	v_readlane_b32 s7, v253, 43
	s_cselect_b64 s[0:1], -1, 0
	s_cmp_gt_i32 s7, 63
	s_cselect_b64 s[4:5], -1, 0
	s_and_b64 s[0:1], s[0:1], s[4:5]
	s_andn2_b64 vcc, exec, s[0:1]
	s_cbranch_vccnz .LBB0_584
	s_lshl_b32 s0, s7, 3
	v_readlane_b32 s4, v253, 45
	s_add_i32 s0, s0, s4
	s_add_i32 s6, s0, 0xfffffe00
	s_cmpk_gt_i32 s6, 0xf7f
	v_readlane_b32 s5, v253, 46
	s_cbranch_scc1 .LBB0_584
	s_mov_b32 s4, s6
	s_movk_i32 s24, 0x600
	s_movk_i32 s25, 0xf80
	v_readlane_b32 s0, v253, 45
	s_mulk_i32 s0, 0x4200
	s_add_i32 s0, s97, s0
	v_readlane_b32 s22, v253, 41
	v_readlane_b32 s23, v253, 42
	v_readlane_b32 s6, v252, 1
	v_readlane_b32 s7, v252, 2
	s_load_dwordx4 s[8:11], s[6:7], 0x48
	s_load_dwordx2 s[14:15], s[6:7], 0x60
	v_lshlrev_b32_e32 v0, 1, v238
	v_and_b32_e32 v8, 3, v237
	v_and_or_b32 v8, v0, 24, v8
	v_lshrrev_b32_e32 v9, 2, v237
	v_and_or_b32 v9, v9, 4, v8
	v_lshlrev_b32_e32 v9, 2, v9
	v_lshrrev_b32_e32 v7, 5, v238
	v_lshrrev_b32_e32 v12, 3, v238
	v_lshlrev_b32_e32 v11, 3, v238
	v_and_b32_e32 v11, 56, v11
	v_lshlrev_b32_e32 v10, 1, v11
	v_lshl_add_u32 v4, v12, 11, v10
	v_and_b32_e32 v10, 31, v237
	v_lshlrev_b32_e32 v8, 2, v10
	v_mul_u32_u24_e32 v2, 0x84, v7
	v_add3_u32 v13, s0, v8, v2
	v_add_u32_e32 v14, 0x400, v13
	v_add_u32_e32 v15, 0x800, v13
	v_add_u32_e32 v16, 0xc00, v13
	v_add_u32_e32 v17, 0x1000, v13
	v_add_u32_e32 v18, 0x1400, v13
	v_add_u32_e32 v19, 0x1800, v13
	v_add_u32_e32 v20, 0x1c00, v13
	v_bfe_u32 v3, v10, 2, 1
	v_mul_u32_u24_e32 v3, 0x2100, v3
	v_lshrrev_b32_e32 v0, 3, v10
	v_lshlrev_b32_e32 v0, 2, v0
	v_and_b32_e32 v10, 3, v10
	v_or_b32_e32 v0, v0, v10
	v_lshlrev_b32_e32 v0, 2, v0
	v_add3_u32 v0, v0, v2, v3
	v_add_u32_e32 v144, s0, v0
	v_add_u32_e32 v145, 0x400, v144
	v_add_u32_e32 v146, 0x800, v144
	v_add_u32_e32 v147, 0xc00, v144
	v_add_u32_e32 v148, 0x1000, v144
	v_add_u32_e32 v149, 0x1400, v144
	v_add_u32_e32 v150, 0x1800, v144
	v_add_u32_e32 v151, 0x1c00, v144
	v_add_u32_e32 v152, 64, v144
	v_add_u32_e32 v153, 64, v145
	v_add_u32_e32 v154, 64, v146
	v_add_u32_e32 v155, 64, v147
	v_add_u32_e32 v156, 64, v148
	v_add_u32_e32 v157, 64, v149
	v_add_u32_e32 v158, 64, v150
	v_add_u32_e32 v159, 64, v151
	v_mul_u32_u24_e32 v10, 0x84, v11
	v_lshlrev_b32_e32 v2, 2, v12
	v_add3_u32 v21, s0, v10, v2
	v_mov_b32_e32 v11, v1
	s_waitcnt lgkmcnt(0)
	v_mul_u32_u24_e32 v10, 0x2c00, v7
	v_add_u32_e32 v10, v10, v8
	v_lshl_add_u64 v[136:137], s[8:9], 0, v[10:11]
	v_lshl_add_u64 v[138:139], s[10:11], 0, v[10:11]
	v_mul_u32_u24_e32 v10, 0x2400, v7
	v_add_u32_e32 v10, v10, v9
	v_lshl_add_u64 v[140:141], s[14:15], 0, v[10:11]
	s_cmpk_lt_u32 s4, 0xb00
	s_cbranch_scc0 .Lcvc_in1
	s_cmpk_gt_u32 s4, 0x57f
	s_cselect_b32 s5, 1, 0
	s_mul_i32 s6, s5, 0x580
	s_sub_i32 s6, s4, s6
	s_mul_i32 s7, s6, 0x2e9
	s_lshr_b32 s7, s7, 16
	s_mul_i32 s8, s7, 0x58
	s_sub_i32 s6, s6, s8
	s_lshr_b32 s8, s6, 2
	s_and_b32 s9, s6, 3
	s_lshl_b32 s10, s8, 9
	s_lshl_b32 s11, s9, 7
	s_add_i32 s10, s10, s11
	s_mul_i32 s11, s5, 0xb00000
	s_add_u32 s10, s10, s11
	s_add_u32 s10, s10, 0x1600000
	s_mul_i32 s11, s7, 0xb0000
	s_add_u32 s10, s10, s11
	s_mov_b32 s11, 0
	v_lshl_add_u64 v[22:23], v[136:137], 0, s[10:11]
	v_lshl_add_u64 v[142:143], v[138:139], 0, s[10:11]
	s_mov_b64 s[26:27], 0x5800
	s_lshl_b32 s8, s8, 3
	s_add_i32 s8, s8, s9
	s_mul_i32 s9, s5, 0xf80000
	s_lshl_b32 s8, s8, 16
	s_add_u32 s8, s8, s9
	s_lshl_b32 s9, s7, 7
	s_add_u32 s8, s8, s9
	s_add_u32 s8, s8, 0x3780000
	s_add_u32 s12, s22, s8
	s_addc_u32 s13, s23, 0
	s_mov_b32 s1, 1
	global_load_dword v24, v[22:23], off nt
	v_lshl_add_u64 v[22:23], v[22:23], 0, s[26:27]
	global_load_dword v25, v[22:23], off nt
	v_lshl_add_u64 v[22:23], v[22:23], 0, s[26:27]
	global_load_dword v26, v[22:23], off nt
	v_lshl_add_u64 v[22:23], v[22:23], 0, s[26:27]
	global_load_dword v27, v[22:23], off nt
	v_lshl_add_u64 v[22:23], v[22:23], 0, s[26:27]
	global_load_dword v28, v[22:23], off nt
	v_lshl_add_u64 v[22:23], v[22:23], 0, s[26:27]
	global_load_dword v29, v[22:23], off nt
	v_lshl_add_u64 v[22:23], v[22:23], 0, s[26:27]
	global_load_dword v30, v[22:23], off nt
	v_lshl_add_u64 v[22:23], v[22:23], 0, s[26:27]
	global_load_dword v31, v[22:23], off nt
	v_lshl_add_u64 v[22:23], v[22:23], 0, s[26:27]
	global_load_dword v32, v[22:23], off nt
	v_lshl_add_u64 v[22:23], v[22:23], 0, s[26:27]
	global_load_dword v33, v[22:23], off nt
	v_lshl_add_u64 v[22:23], v[22:23], 0, s[26:27]
	global_load_dword v34, v[22:23], off nt
	v_lshl_add_u64 v[22:23], v[22:23], 0, s[26:27]
	global_load_dword v35, v[22:23], off nt
	v_lshl_add_u64 v[22:23], v[22:23], 0, s[26:27]
	global_load_dword v36, v[22:23], off nt
	v_lshl_add_u64 v[22:23], v[22:23], 0, s[26:27]
	global_load_dword v37, v[22:23], off nt
	v_lshl_add_u64 v[22:23], v[22:23], 0, s[26:27]
	global_load_dword v38, v[22:23], off nt
	v_lshl_add_u64 v[22:23], v[22:23], 0, s[26:27]
	global_load_dword v39, v[22:23], off nt
	v_lshl_add_u64 v[22:23], v[22:23], 0, s[26:27]
	global_load_dword v40, v[22:23], off nt
	v_lshl_add_u64 v[22:23], v[22:23], 0, s[26:27]
	global_load_dword v41, v[22:23], off nt
	v_lshl_add_u64 v[22:23], v[22:23], 0, s[26:27]
	global_load_dword v42, v[22:23], off nt
	v_lshl_add_u64 v[22:23], v[22:23], 0, s[26:27]
	global_load_dword v43, v[22:23], off nt
	v_lshl_add_u64 v[22:23], v[22:23], 0, s[26:27]
	global_load_dword v44, v[22:23], off nt
	v_lshl_add_u64 v[22:23], v[22:23], 0, s[26:27]
	global_load_dword v45, v[22:23], off nt
	v_lshl_add_u64 v[22:23], v[22:23], 0, s[26:27]
	global_load_dword v46, v[22:23], off nt
	v_lshl_add_u64 v[22:23], v[22:23], 0, s[26:27]
	global_load_dword v47, v[22:23], off nt
	v_lshl_add_u64 v[22:23], v[22:23], 0, s[26:27]
	global_load_dword v48, v[22:23], off nt
	v_lshl_add_u64 v[22:23], v[22:23], 0, s[26:27]
	global_load_dword v49, v[22:23], off nt
	v_lshl_add_u64 v[22:23], v[22:23], 0, s[26:27]
	global_load_dword v50, v[22:23], off nt
	v_lshl_add_u64 v[22:23], v[22:23], 0, s[26:27]
	global_load_dword v51, v[22:23], off nt
	v_lshl_add_u64 v[22:23], v[22:23], 0, s[26:27]
	global_load_dword v52, v[22:23], off nt
	v_lshl_add_u64 v[22:23], v[22:23], 0, s[26:27]
	global_load_dword v53, v[22:23], off nt
	v_lshl_add_u64 v[22:23], v[22:23], 0, s[26:27]
	global_load_dword v54, v[22:23], off nt
	v_lshl_add_u64 v[22:23], v[22:23], 0, s[26:27]
	global_load_dword v55, v[22:23], off nt
	global_load_dword v56, v[142:143], off nt
	v_lshl_add_u64 v[142:143], v[142:143], 0, s[26:27]
	global_load_dword v57, v[142:143], off nt
	v_lshl_add_u64 v[142:143], v[142:143], 0, s[26:27]
	global_load_dword v58, v[142:143], off nt
	v_lshl_add_u64 v[142:143], v[142:143], 0, s[26:27]
	global_load_dword v59, v[142:143], off nt
	v_lshl_add_u64 v[142:143], v[142:143], 0, s[26:27]
	global_load_dword v60, v[142:143], off nt
	v_lshl_add_u64 v[142:143], v[142:143], 0, s[26:27]
	global_load_dword v61, v[142:143], off nt
	v_lshl_add_u64 v[142:143], v[142:143], 0, s[26:27]
	global_load_dword v62, v[142:143], off nt
	v_lshl_add_u64 v[142:143], v[142:143], 0, s[26:27]
	global_load_dword v63, v[142:143], off nt
	v_lshl_add_u64 v[142:143], v[142:143], 0, s[26:27]
	global_load_dword v64, v[142:143], off nt
	v_lshl_add_u64 v[142:143], v[142:143], 0, s[26:27]
	global_load_dword v65, v[142:143], off nt
	v_lshl_add_u64 v[142:143], v[142:143], 0, s[26:27]
	global_load_dword v66, v[142:143], off nt
	v_lshl_add_u64 v[142:143], v[142:143], 0, s[26:27]
	global_load_dword v67, v[142:143], off nt
	v_lshl_add_u64 v[142:143], v[142:143], 0, s[26:27]
	global_load_dword v68, v[142:143], off nt
	v_lshl_add_u64 v[142:143], v[142:143], 0, s[26:27]
	global_load_dword v69, v[142:143], off nt
	v_lshl_add_u64 v[142:143], v[142:143], 0, s[26:27]
	global_load_dword v70, v[142:143], off nt
	v_lshl_add_u64 v[142:143], v[142:143], 0, s[26:27]
	global_load_dword v71, v[142:143], off nt
	v_lshl_add_u64 v[142:143], v[142:143], 0, s[26:27]
	global_load_dword v72, v[142:143], off nt
	v_lshl_add_u64 v[142:143], v[142:143], 0, s[26:27]
	global_load_dword v73, v[142:143], off nt
	v_lshl_add_u64 v[142:143], v[142:143], 0, s[26:27]
	global_load_dword v74, v[142:143], off nt
	v_lshl_add_u64 v[142:143], v[142:143], 0, s[26:27]
	global_load_dword v75, v[142:143], off nt
	v_lshl_add_u64 v[142:143], v[142:143], 0, s[26:27]
	global_load_dword v76, v[142:143], off nt
	v_lshl_add_u64 v[142:143], v[142:143], 0, s[26:27]
	global_load_dword v77, v[142:143], off nt
	v_lshl_add_u64 v[142:143], v[142:143], 0, s[26:27]
	global_load_dword v78, v[142:143], off nt
	v_lshl_add_u64 v[142:143], v[142:143], 0, s[26:27]
	global_load_dword v79, v[142:143], off nt
	v_lshl_add_u64 v[142:143], v[142:143], 0, s[26:27]
	global_load_dword v80, v[142:143], off nt
	v_lshl_add_u64 v[142:143], v[142:143], 0, s[26:27]
	global_load_dword v81, v[142:143], off nt
	v_lshl_add_u64 v[142:143], v[142:143], 0, s[26:27]
	global_load_dword v82, v[142:143], off nt
	v_lshl_add_u64 v[142:143], v[142:143], 0, s[26:27]
	global_load_dword v83, v[142:143], off nt
	v_lshl_add_u64 v[142:143], v[142:143], 0, s[26:27]
	global_load_dword v84, v[142:143], off nt
	v_lshl_add_u64 v[142:143], v[142:143], 0, s[26:27]
	global_load_dword v85, v[142:143], off nt
	v_lshl_add_u64 v[142:143], v[142:143], 0, s[26:27]
	global_load_dword v86, v[142:143], off nt
	v_lshl_add_u64 v[142:143], v[142:143], 0, s[26:27]
	global_load_dword v87, v[142:143], off nt
	s_branch .Lcvc_e1
.Lcvc_in1:
	s_sub_i32 s6, s4, 0xb00
	s_mul_i32 s7, s6, 0x38f
	s_lshr_b32 s7, s7, 16
	s_mul_i32 s8, s7, 0x48
	s_sub_i32 s6, s6, s8
	s_lshr_b32 s8, s6, 3
	s_lshl_b32 s8, s8, 8
	s_and_b32 s9, s6, 3
	s_lshl_b32 s9, s9, 6
	s_add_i32 s8, s8, s9
	s_bfe_u32 s9, s6, 0x10002
	s_lshl_b32 s9, s9, 5
	s_add_i32 s8, s8, s9
	s_lshl_b32 s8, s8, 2
	s_add_u32 s8, s8, 0x900000
	s_mul_i32 s9, s7, 0x90000
	s_add_u32 s10, s8, s9
	s_mov_b32 s11, 0
	v_lshl_add_u64 v[22:23], v[140:141], 0, s[10:11]
	s_mov_b64 s[26:27], 0x4800
	s_lshl_b32 s8, s6, 16
	s_lshl_b32 s9, s7, 7
	s_add_u32 s8, s8, s9
	s_add_u32 s8, s8, 0x4280000
	s_add_u32 s12, s22, s8
	s_addc_u32 s13, s23, 0
	s_mov_b32 s1, 0
	global_load_dword v24, v[22:23], off nt
	v_lshl_add_u64 v[22:23], v[22:23], 0, s[26:27]
	global_load_dword v25, v[22:23], off nt
	v_lshl_add_u64 v[22:23], v[22:23], 0, s[26:27]
	global_load_dword v26, v[22:23], off nt
	v_lshl_add_u64 v[22:23], v[22:23], 0, s[26:27]
	global_load_dword v27, v[22:23], off nt
	v_lshl_add_u64 v[22:23], v[22:23], 0, s[26:27]
	global_load_dword v28, v[22:23], off nt
	v_lshl_add_u64 v[22:23], v[22:23], 0, s[26:27]
	global_load_dword v29, v[22:23], off nt
	v_lshl_add_u64 v[22:23], v[22:23], 0, s[26:27]
	global_load_dword v30, v[22:23], off nt
	v_lshl_add_u64 v[22:23], v[22:23], 0, s[26:27]
	global_load_dword v31, v[22:23], off nt
	v_lshl_add_u64 v[22:23], v[22:23], 0, s[26:27]
	global_load_dword v32, v[22:23], off nt
	v_lshl_add_u64 v[22:23], v[22:23], 0, s[26:27]
	global_load_dword v33, v[22:23], off nt
	v_lshl_add_u64 v[22:23], v[22:23], 0, s[26:27]
	global_load_dword v34, v[22:23], off nt
	v_lshl_add_u64 v[22:23], v[22:23], 0, s[26:27]
	global_load_dword v35, v[22:23], off nt
	v_lshl_add_u64 v[22:23], v[22:23], 0, s[26:27]
	global_load_dword v36, v[22:23], off nt
	v_lshl_add_u64 v[22:23], v[22:23], 0, s[26:27]
	global_load_dword v37, v[22:23], off nt
	v_lshl_add_u64 v[22:23], v[22:23], 0, s[26:27]
	global_load_dword v38, v[22:23], off nt
	v_lshl_add_u64 v[22:23], v[22:23], 0, s[26:27]
	global_load_dword v39, v[22:23], off nt
	v_lshl_add_u64 v[22:23], v[22:23], 0, s[26:27]
	global_load_dword v40, v[22:23], off nt
	v_lshl_add_u64 v[22:23], v[22:23], 0, s[26:27]
	global_load_dword v41, v[22:23], off nt
	v_lshl_add_u64 v[22:23], v[22:23], 0, s[26:27]
	global_load_dword v42, v[22:23], off nt
	v_lshl_add_u64 v[22:23], v[22:23], 0, s[26:27]
	global_load_dword v43, v[22:23], off nt
	v_lshl_add_u64 v[22:23], v[22:23], 0, s[26:27]
	global_load_dword v44, v[22:23], off nt
	v_lshl_add_u64 v[22:23], v[22:23], 0, s[26:27]
	global_load_dword v45, v[22:23], off nt
	v_lshl_add_u64 v[22:23], v[22:23], 0, s[26:27]
	global_load_dword v46, v[22:23], off nt
	v_lshl_add_u64 v[22:23], v[22:23], 0, s[26:27]
	global_load_dword v47, v[22:23], off nt
	v_lshl_add_u64 v[22:23], v[22:23], 0, s[26:27]
	global_load_dword v48, v[22:23], off nt
	v_lshl_add_u64 v[22:23], v[22:23], 0, s[26:27]
	global_load_dword v49, v[22:23], off nt
	v_lshl_add_u64 v[22:23], v[22:23], 0, s[26:27]
	global_load_dword v50, v[22:23], off nt
	v_lshl_add_u64 v[22:23], v[22:23], 0, s[26:27]
	global_load_dword v51, v[22:23], off nt
	v_lshl_add_u64 v[22:23], v[22:23], 0, s[26:27]
	global_load_dword v52, v[22:23], off nt
	v_lshl_add_u64 v[22:23], v[22:23], 0, s[26:27]
	global_load_dword v53, v[22:23], off nt
	v_lshl_add_u64 v[22:23], v[22:23], 0, s[26:27]
	global_load_dword v54, v[22:23], off nt
	v_lshl_add_u64 v[22:23], v[22:23], 0, s[26:27]
	global_load_dword v55, v[22:23], off nt

.Lcvc_top:
	s_mov_b64 s[20:21], s[12:13]
	s_mov_b32 s0, s1
	s_cmp_eq_u32 s0, 0
	s_cbranch_scc1 .Lcvc_ws
	ds_write2_b32 v144, v24, v25 offset0:0 offset1:66
	ds_write2_b32 v144, v26, v27 offset0:132 offset1:198
	ds_write2_b32 v145, v28, v29 offset0:8 offset1:74
	ds_write2_b32 v145, v30, v31 offset0:140 offset1:206
	ds_write2_b32 v146, v32, v33 offset0:16 offset1:82
	ds_write2_b32 v146, v34, v35 offset0:148 offset1:214
	ds_write2_b32 v147, v36, v37 offset0:24 offset1:90
	ds_write2_b32 v147, v38, v39 offset0:156 offset1:222
	ds_write2_b32 v148, v40, v41 offset0:32 offset1:98
	ds_write2_b32 v148, v42, v43 offset0:164 offset1:230
	ds_write2_b32 v149, v44, v45 offset0:40 offset1:106
	ds_write2_b32 v149, v46, v47 offset0:172 offset1:238
	ds_write2_b32 v150, v48, v49 offset0:48 offset1:114
	ds_write2_b32 v150, v50, v51 offset0:180 offset1:246
	ds_write2_b32 v151, v52, v53 offset0:56 offset1:122
	ds_write2_b32 v151, v54, v55 offset0:188 offset1:254
	ds_write2_b32 v152, v56, v57 offset0:0 offset1:66
	ds_write2_b32 v152, v58, v59 offset0:132 offset1:198
	ds_write2_b32 v153, v60, v61 offset0:8 offset1:74
	ds_write2_b32 v153, v62, v63 offset0:140 offset1:206
	ds_write2_b32 v154, v64, v65 offset0:16 offset1:82
	ds_write2_b32 v154, v66, v67 offset0:148 offset1:214
	ds_write2_b32 v155, v68, v69 offset0:24 offset1:90
	ds_write2_b32 v155, v70, v71 offset0:156 offset1:222
	ds_write2_b32 v156, v72, v73 offset0:32 offset1:98
	ds_write2_b32 v156, v74, v75 offset0:164 offset1:230
	ds_write2_b32 v157, v76, v77 offset0:40 offset1:106
	ds_write2_b32 v157, v78, v79 offset0:172 offset1:238
	ds_write2_b32 v158, v80, v81 offset0:48 offset1:114
	ds_write2_b32 v158, v82, v83 offset0:180 offset1:246
	ds_write2_b32 v159, v84, v85 offset0:56 offset1:122
	ds_write2_b32 v159, v86, v87 offset0:188 offset1:254
	s_branch .Lcvc_wd
.Lcvc_ws:
	ds_write2_b32 v13, v24, v25 offset0:0 offset1:66
	ds_write2_b32 v13, v26, v27 offset0:132 offset1:198
	ds_write2_b32 v14, v28, v29 offset0:8 offset1:74
	ds_write2_b32 v14, v30, v31 offset0:140 offset1:206
	ds_write2_b32 v15, v32, v33 offset0:16 offset1:82
	ds_write2_b32 v15, v34, v35 offset0:148 offset1:214
	ds_write2_b32 v16, v36, v37 offset0:24 offset1:90
	ds_write2_b32 v16, v38, v39 offset0:156 offset1:222
	ds_write2_b32 v17, v40, v41 offset0:32 offset1:98
	ds_write2_b32 v17, v42, v43 offset0:164 offset1:230
	ds_write2_b32 v18, v44, v45 offset0:40 offset1:106
	ds_write2_b32 v18, v46, v47 offset0:172 offset1:238
	ds_write2_b32 v19, v48, v49 offset0:48 offset1:114
	ds_write2_b32 v19, v50, v51 offset0:180 offset1:246
	ds_write2_b32 v20, v52, v53 offset0:56 offset1:122
	ds_write2_b32 v20, v54, v55 offset0:188 offset1:254
.Lcvc_wd:
	s_add_i32 s4, s4, s24
	s_cmp_lt_u32 s4, s25
	s_cbranch_scc0 .Lcvc_noload
	s_cmpk_lt_u32 s4, 0xb00
	s_cbranch_scc0 .Lcvc_in2
	s_cmpk_gt_u32 s4, 0x57f
	s_cselect_b32 s5, 1, 0
	s_mul_i32 s6, s5, 0x580
	s_sub_i32 s6, s4, s6
	s_mul_i32 s7, s6, 0x2e9
	s_lshr_b32 s7, s7, 16
	s_mul_i32 s8, s7, 0x58
	s_sub_i32 s6, s6, s8
	s_lshr_b32 s8, s6, 2
	s_and_b32 s9, s6, 3
	s_lshl_b32 s10, s8, 9
	s_lshl_b32 s11, s9, 7
	s_add_i32 s10, s10, s11
	s_mul_i32 s11, s5, 0xb00000
	s_add_u32 s10, s10, s11
	s_add_u32 s10, s10, 0x1600000
	s_mul_i32 s11, s7, 0xb0000
	s_add_u32 s10, s10, s11
	s_mov_b32 s11, 0
	v_lshl_add_u64 v[22:23], v[136:137], 0, s[10:11]
	v_lshl_add_u64 v[142:143], v[138:139], 0, s[10:11]
	s_mov_b64 s[26:27], 0x5800
	s_lshl_b32 s8, s8, 3
	s_add_i32 s8, s8, s9
	s_mul_i32 s9, s5, 0xf80000
	s_lshl_b32 s8, s8, 16
	s_add_u32 s8, s8, s9
	s_lshl_b32 s9, s7, 7
	s_add_u32 s8, s8, s9
	s_add_u32 s8, s8, 0x3780000
	s_add_u32 s12, s22, s8
	s_addc_u32 s13, s23, 0
	s_mov_b32 s1, 1
	global_load_dword v24, v[22:23], off nt
	v_lshl_add_u64 v[22:23], v[22:23], 0, s[26:27]
	global_load_dword v25, v[22:23], off nt
	v_lshl_add_u64 v[22:23], v[22:23], 0, s[26:27]
	global_load_dword v26, v[22:23], off nt
	v_lshl_add_u64 v[22:23], v[22:23], 0, s[26:27]
	global_load_dword v27, v[22:23], off nt
	v_lshl_add_u64 v[22:23], v[22:23], 0, s[26:27]
	global_load_dword v28, v[22:23], off nt
	v_lshl_add_u64 v[22:23], v[22:23], 0, s[26:27]
	global_load_dword v29, v[22:23], off nt
	v_lshl_add_u64 v[22:23], v[22:23], 0, s[26:27]
	global_load_dword v30, v[22:23], off nt
	v_lshl_add_u64 v[22:23], v[22:23], 0, s[26:27]
	global_load_dword v31, v[22:23], off nt
	v_lshl_add_u64 v[22:23], v[22:23], 0, s[26:27]
	global_load_dword v32, v[22:23], off nt
	v_lshl_add_u64 v[22:23], v[22:23], 0, s[26:27]
	global_load_dword v33, v[22:23], off nt
	v_lshl_add_u64 v[22:23], v[22:23], 0, s[26:27]
	global_load_dword v34, v[22:23], off nt
	v_lshl_add_u64 v[22:23], v[22:23], 0, s[26:27]
	global_load_dword v35, v[22:23], off nt
	v_lshl_add_u64 v[22:23], v[22:23], 0, s[26:27]
	global_load_dword v36, v[22:23], off nt
	v_lshl_add_u64 v[22:23], v[22:23], 0, s[26:27]
	global_load_dword v37, v[22:23], off nt
	v_lshl_add_u64 v[22:23], v[22:23], 0, s[26:27]
	global_load_dword v38, v[22:23], off nt
	v_lshl_add_u64 v[22:23], v[22:23], 0, s[26:27]
	global_load_dword v39, v[22:23], off nt
	v_lshl_add_u64 v[22:23], v[22:23], 0, s[26:27]
	global_load_dword v40, v[22:23], off nt
	v_lshl_add_u64 v[22:23], v[22:23], 0, s[26:27]
	global_load_dword v41, v[22:23], off nt
	v_lshl_add_u64 v[22:23], v[22:23], 0, s[26:27]
	global_load_dword v42, v[22:23], off nt
	v_lshl_add_u64 v[22:23], v[22:23], 0, s[26:27]
	global_load_dword v43, v[22:23], off nt
	v_lshl_add_u64 v[22:23], v[22:23], 0, s[26:27]
	global_load_dword v44, v[22:23], off nt
	v_lshl_add_u64 v[22:23], v[22:23], 0, s[26:27]
	global_load_dword v45, v[22:23], off nt
	v_lshl_add_u64 v[22:23], v[22:23], 0, s[26:27]
	global_load_dword v46, v[22:23], off nt
	v_lshl_add_u64 v[22:23], v[22:23], 0, s[26:27]
	global_load_dword v47, v[22:23], off nt
	v_lshl_add_u64 v[22:23], v[22:23], 0, s[26:27]
	global_load_dword v48, v[22:23], off nt
	v_lshl_add_u64 v[22:23], v[22:23], 0, s[26:27]
	global_load_dword v49, v[22:23], off nt
	v_lshl_add_u64 v[22:23], v[22:23], 0, s[26:27]
	global_load_dword v50, v[22:23], off nt
	v_lshl_add_u64 v[22:23], v[22:23], 0, s[26:27]
	global_load_dword v51, v[22:23], off nt
	v_lshl_add_u64 v[22:23], v[22:23], 0, s[26:27]
	global_load_dword v52, v[22:23], off nt
	v_lshl_add_u64 v[22:23], v[22:23], 0, s[26:27]
	global_load_dword v53, v[22:23], off nt
	v_lshl_add_u64 v[22:23], v[22:23], 0, s[26:27]
	global_load_dword v54, v[22:23], off nt
	v_lshl_add_u64 v[22:23], v[22:23], 0, s[26:27]
	global_load_dword v55, v[22:23], off nt
	global_load_dword v56, v[142:143], off nt
	v_lshl_add_u64 v[142:143], v[142:143], 0, s[26:27]
	global_load_dword v57, v[142:143], off nt
	v_lshl_add_u64 v[142:143], v[142:143], 0, s[26:27]
	global_load_dword v58, v[142:143], off nt
	v_lshl_add_u64 v[142:143], v[142:143], 0, s[26:27]
	global_load_dword v59, v[142:143], off nt
	v_lshl_add_u64 v[142:143], v[142:143], 0, s[26:27]
	global_load_dword v60, v[142:143], off nt
	v_lshl_add_u64 v[142:143], v[142:143], 0, s[26:27]
	global_load_dword v61, v[142:143], off nt
	v_lshl_add_u64 v[142:143], v[142:143], 0, s[26:27]
	global_load_dword v62, v[142:143], off nt
	v_lshl_add_u64 v[142:143], v[142:143], 0, s[26:27]
	global_load_dword v63, v[142:143], off nt
	v_lshl_add_u64 v[142:143], v[142:143], 0, s[26:27]
	global_load_dword v64, v[142:143], off nt
	v_lshl_add_u64 v[142:143], v[142:143], 0, s[26:27]
	global_load_dword v65, v[142:143], off nt
	v_lshl_add_u64 v[142:143], v[142:143], 0, s[26:27]
	global_load_dword v66, v[142:143], off nt
	v_lshl_add_u64 v[142:143], v[142:143], 0, s[26:27]
	global_load_dword v67, v[142:143], off nt
	v_lshl_add_u64 v[142:143], v[142:143], 0, s[26:27]
	global_load_dword v68, v[142:143], off nt
	v_lshl_add_u64 v[142:143], v[142:143], 0, s[26:27]
	global_load_dword v69, v[142:143], off nt
	v_lshl_add_u64 v[142:143], v[142:143], 0, s[26:27]
	global_load_dword v70, v[142:143], off nt
	v_lshl_add_u64 v[142:143], v[142:143], 0, s[26:27]
	global_load_dword v71, v[142:143], off nt
	v_lshl_add_u64 v[142:143], v[142:143], 0, s[26:27]
	global_load_dword v72, v[142:143], off nt
	v_lshl_add_u64 v[142:143], v[142:143], 0, s[26:27]
	global_load_dword v73, v[142:143], off nt
	v_lshl_add_u64 v[142:143], v[142:143], 0, s[26:27]
	global_load_dword v74, v[142:143], off nt
	v_lshl_add_u64 v[142:143], v[142:143], 0, s[26:27]
	global_load_dword v75, v[142:143], off nt
	v_lshl_add_u64 v[142:143], v[142:143], 0, s[26:27]
	global_load_dword v76, v[142:143], off nt
	v_lshl_add_u64 v[142:143], v[142:143], 0, s[26:27]
	global_load_dword v77, v[142:143], off nt
	v_lshl_add_u64 v[142:143], v[142:143], 0, s[26:27]
	global_load_dword v78, v[142:143], off nt
	v_lshl_add_u64 v[142:143], v[142:143], 0, s[26:27]
	global_load_dword v79, v[142:143], off nt
	v_lshl_add_u64 v[142:143], v[142:143], 0, s[26:27]
	global_load_dword v80, v[142:143], off nt
	v_lshl_add_u64 v[142:143], v[142:143], 0, s[26:27]
	global_load_dword v81, v[142:143], off nt
	v_lshl_add_u64 v[142:143], v[142:143], 0, s[26:27]
	global_load_dword v82, v[142:143], off nt
	v_lshl_add_u64 v[142:143], v[142:143], 0, s[26:27]
	global_load_dword v83, v[142:143], off nt
	v_lshl_add_u64 v[142:143], v[142:143], 0, s[26:27]
	global_load_dword v84, v[142:143], off nt
	v_lshl_add_u64 v[142:143], v[142:143], 0, s[26:27]
	global_load_dword v85, v[142:143], off nt
	v_lshl_add_u64 v[142:143], v[142:143], 0, s[26:27]
	global_load_dword v86, v[142:143], off nt
	v_lshl_add_u64 v[142:143], v[142:143], 0, s[26:27]
	global_load_dword v87, v[142:143], off nt
	s_branch .Lcvc_e2

.Lcvc_e2:
.Lcvc_noload:
	s_waitcnt lgkmcnt(0)
	ds_read2_b32 v[88:89], v21 offset0:0 offset1:8
	ds_read2_b32 v[90:91], v21 offset0:33 offset1:41
	ds_read2_b32 v[92:93], v21 offset0:66 offset1:74
	ds_read2_b32 v[94:95], v21 offset0:99 offset1:107
	ds_read2_b32 v[96:97], v21 offset0:132 offset1:140
	ds_read2_b32 v[98:99], v21 offset0:165 offset1:173
	ds_read2_b32 v[100:101], v21 offset0:198 offset1:206
	ds_read2_b32 v[102:103], v21 offset0:231 offset1:239
	ds_read2_b32 v[104:105], v21 offset0:16 offset1:24
	ds_read2_b32 v[106:107], v21 offset0:49 offset1:57
	ds_read2_b32 v[108:109], v21 offset0:82 offset1:90
	ds_read2_b32 v[110:111], v21 offset0:115 offset1:123
	ds_read2_b32 v[112:113], v21 offset0:148 offset1:156
	ds_read2_b32 v[114:115], v21 offset0:181 offset1:189
	ds_read2_b32 v[116:117], v21 offset0:214 offset1:222
	ds_read2_b32 v[118:119], v21 offset0:247 offset1:255
	s_waitcnt lgkmcnt(8)
	v_cvt_pk_bf16_f32 v120, v88, v90
	v_cvt_pk_bf16_f32 v121, v92, v94
	v_cvt_pk_bf16_f32 v122, v96, v98
	v_cvt_pk_bf16_f32 v123, v100, v102
	v_cvt_pk_bf16_f32 v124, v89, v91
	v_cvt_pk_bf16_f32 v125, v93, v95
	v_cvt_pk_bf16_f32 v126, v97, v99
	v_cvt_pk_bf16_f32 v127, v101, v103
	global_store_dwordx4 v4, v[120:123], s[20:21]
	s_add_u32 s20, s20, 0x4000
	s_addc_u32 s21, s21, 0
	global_store_dwordx4 v4, v[124:127], s[20:21]
	s_add_u32 s20, s20, 0x4000
	s_addc_u32 s21, s21, 0
	s_waitcnt lgkmcnt(0)
	v_cvt_pk_bf16_f32 v128, v104, v106
	v_cvt_pk_bf16_f32 v129, v108, v110
	v_cvt_pk_bf16_f32 v130, v112, v114
	v_cvt_pk_bf16_f32 v131, v116, v118
	v_cvt_pk_bf16_f32 v132, v105, v107
	v_cvt_pk_bf16_f32 v133, v109, v111
	v_cvt_pk_bf16_f32 v134, v113, v115
	v_cvt_pk_bf16_f32 v135, v117, v119
	global_store_dwordx4 v4, v[128:131], s[20:21]
	s_add_u32 s20, s20, 0x4000
	s_addc_u32 s21, s21, 0
	global_store_dwordx4 v4, v[132:135], s[20:21]
	s_cmp_eq_u32 s0, 0
	s_cbranch_scc1 .Lcvc_nosec
	s_add_u32 s20, s20, 0x34000
	s_addc_u32 s21, s21, 0
	v_add_u32_e32 v21, 0x2100, v21
	ds_read2_b32 v[88:89], v21 offset0:0 offset1:8
	ds_read2_b32 v[90:91], v21 offset0:33 offset1:41
	ds_read2_b32 v[92:93], v21 offset0:66 offset1:74
	ds_read2_b32 v[94:95], v21 offset0:99 offset1:107
	ds_read2_b32 v[96:97], v21 offset0:132 offset1:140
	ds_read2_b32 v[98:99], v21 offset0:165 offset1:173
	ds_read2_b32 v[100:101], v21 offset0:198 offset1:206
	ds_read2_b32 v[102:103], v21 offset0:231 offset1:239
	ds_read2_b32 v[104:105], v21 offset0:16 offset1:24
	ds_read2_b32 v[106:107], v21 offset0:49 offset1:57
	ds_read2_b32 v[108:109], v21 offset0:82 offset1:90
	ds_read2_b32 v[110:111], v21 offset0:115 offset1:123
	ds_read2_b32 v[112:113], v21 offset0:148 offset1:156
	ds_read2_b32 v[114:115], v21 offset0:181 offset1:189
	ds_read2_b32 v[116:117], v21 offset0:214 offset1:222
	ds_read2_b32 v[118:119], v21 offset0:247 offset1:255
	s_waitcnt lgkmcnt(8)
	v_cvt_pk_bf16_f32 v120, v88, v90
	v_cvt_pk_bf16_f32 v121, v92, v94
	v_cvt_pk_bf16_f32 v122, v96, v98
	v_cvt_pk_bf16_f32 v123, v100, v102
	v_cvt_pk_bf16_f32 v124, v89, v91
	v_cvt_pk_bf16_f32 v125, v93, v95
	v_cvt_pk_bf16_f32 v126, v97, v99
	v_cvt_pk_bf16_f32 v127, v101, v103
	global_store_dwordx4 v4, v[120:123], s[20:21]
	s_add_u32 s20, s20, 0x4000
	s_addc_u32 s21, s21, 0
	global_store_dwordx4 v4, v[124:127], s[20:21]
	s_add_u32 s20, s20, 0x4000
	s_addc_u32 s21, s21, 0
	s_waitcnt lgkmcnt(0)
	v_cvt_pk_bf16_f32 v128, v104, v106
	v_cvt_pk_bf16_f32 v129, v108, v110
	v_cvt_pk_bf16_f32 v130, v112, v114
	v_cvt_pk_bf16_f32 v131, v116, v118
	v_cvt_pk_bf16_f32 v132, v105, v107
	v_cvt_pk_bf16_f32 v133, v109, v111
	v_cvt_pk_bf16_f32 v134, v113, v115
	v_cvt_pk_bf16_f32 v135, v117, v119
	global_store_dwordx4 v4, v[128:131], s[20:21]
	s_add_u32 s20, s20, 0x4000
	s_addc_u32 s21, s21, 0
	global_store_dwordx4 v4, v[132:135], s[20:21]
	v_subrev_u32_e32 v21, 0x2100, v21
.Lcvc_nosec:
	s_cmp_lt_u32 s4, s25
	s_cbranch_scc0 .Lcvc_done
	s_waitcnt vmcnt(4)
	s_branch .Lcvc_top
.Lcvc_done:
	s_branch .LBB0_583
.LBB0_570:
	s_mov_b64 s[4:5], 0
	s_mov_b64 s[8:9], 0
